# all fp8 gate units in part 1 (4 per WG), pooling+GLA-pre on all 256 WGs in part 2
# speedup vs baseline: 1.0032x; 1.0001x over previous
; __global__ void __launch_bounds__(NWAVES * 64, 2) mega_fwd(Args A) {
;     ...
;             unsigned char* XB8 = ws + WS_X;
; #pragma unroll 1
;             for (int part = 0; part < 3; ++part) {
;                 bool do16, do8; int i16, n16, g8, c8, i8, n8;
;                 if (std256) { do16 = part == 0 || (part == 1 && bx < 64); i16 = part ? 2 : 0; n16 = part ? 1 : 2;
;                               do8 = (part == 1 && bx >= 64) || (part == 2 && bx < 128); g8 = part == 1 ? 192 : 128; c8 = part == 1 ? bx - 64 : bx; i8 = part == 1 ? 0 : 3; n8 = part == 1 ? 2 : 3; }
;                 else { do16 = part == 0; i16 = 0; n16 = 1 << 20; do8 = part == 1; g8 = G; c8 = bx; i8 = 0; n8 = 1 << 20; }
;                 if (do16) { pg8::Gemm g{H, (const bf16*)(wl + LW_WIN), NTOK, C_GATE, DM}; pg8::RangeOrder S; S.init(NTOK, C_GATE, G, bx); S.i0 = i16; S.n = n16;
;                     pg8::EpiProj E{PROJ, NPROJ, (const float*)A.in[7] + (size_t)l * 6144, 1 << 20, ssq, 1.0f};
;                     pg8::gemm_phase<pg8::EpiProj, pg8::RangeOrder, true, true>(lds + RING_OFF, g, S, E); }
;                 if (do8) { pg8::Gemm g{(const bf16*)XB8, (const bf16*)(wl + LW_WIN + WIN8_OFF), NTOK, 6144, DM / 2}; pg8::RangeOrder S; S.init(NTOK, 6144, g8, c8); S.i0 = i8; S.n = n8;
;                     pg8::EpiGate8 E{(unsigned char*)(PROJ + C_GATE), NPROJ * 2, (const float*)A.in[7] + (size_t)l * 6144, ssq, 1.0f / 2048.0f};
;                     pg8::gemm_phase<pg8::EpiGate8, pg8::RangeOrder, true, true, true>(lds + RING_OFF, g, S, E); }
;                 if (part == 1) xcd_barrier(bar);
;                 if (part == 2 && (!std256 || bx >= 128)) { const int mb = std256 ? bx - 128 : bx, ms = std256 ? 128 : G;
.LBB0_284:
	v_writelane_b32 v252, s64, 42
	s_nop 1
	v_writelane_b32 v252, s65, 43
	v_writelane_b32 v252, s66, 44
	v_writelane_b32 v252, s67, 45
	v_writelane_b32 v252, s68, 46
	v_writelane_b32 v252, s69, 47
	v_writelane_b32 v252, s70, 48
	v_writelane_b32 v252, s71, 49
	v_writelane_b32 v252, s72, 50
	v_writelane_b32 v252, s73, 51
	v_writelane_b32 v252, s74, 52
	v_writelane_b32 v252, s75, 53
	v_writelane_b32 v252, s76, 54
	v_writelane_b32 v252, s77, 55
	v_writelane_b32 v252, s78, 56
	v_writelane_b32 v252, s79, 57
	s_or_b64 exec, exec, s[0:1]
	s_cmpk_lg_i32 s95, 0x100
	s_cselect_b64 s[0:1], -1, 0
	s_and_b64 s[0:1], s[0:1], exec
	s_cselect_b32 s69, s95, 0x100
	s_add_i32 s4, s97, 0xffffff80
	s_cmpk_lg_i32 s95, 0x100
	s_cselect_b64 s[0:1], -1, 0
	s_and_b64 s[2:3], s[0:1], exec
	s_cselect_b32 s20, s97, s97
	v_readlane_b32 s4, v252, 2
	v_readlane_b32 s18, v252, 16
	v_readlane_b32 s19, v252, 17
	s_add_u32 s74, s18, 0x10000
	s_addc_u32 s2, s19, 0
	v_readlane_b32 s5, v252, 3
	v_readlane_b32 s6, v252, 4
	v_readlane_b32 s7, v252, 5
	v_readlane_b32 s8, v252, 6
	v_readlane_b32 s9, v252, 7
	v_readlane_b32 s10, v252, 8
	v_readlane_b32 s11, v252, 9
	v_readlane_b32 s12, v252, 10
	v_readlane_b32 s13, v252, 11
	v_readlane_b32 s14, v252, 12
	v_readlane_b32 s15, v252, 13
	v_readlane_b32 s16, v252, 14
	v_readlane_b32 s17, v252, 15
	v_writelane_b32 v252, s2, 58
	s_add_u32 s2, s18, 0x35e00000
	s_addc_u32 s3, s19, 0
	s_add_u32 s88, s18, 0x3b600000
	s_addc_u32 s89, s19, 0
	v_writelane_b32 v252, s2, 59
	s_add_u32 s12, s18, 0x45e00000
	s_addc_u32 s13, s19, 0
	v_writelane_b32 v252, s3, 60
	v_writelane_b32 v252, s12, 61
	s_add_u32 s2, s18, 0x4c200000
	v_writelane_b32 v252, s13, 62
	s_addc_u32 s3, s19, 0
	v_writelane_b32 v252, s2, 63
	s_waitcnt vmcnt(15)
	v_mov_b32_e32 v3, 0
	v_mov_b32_e32 v216, 1
	v_writelane_b32 v253, s3, 0
	s_add_u32 s2, s18, 0x4e200000
	s_addc_u32 s3, s19, 0
	v_writelane_b32 v253, s2, 1
	v_mov_b32_e32 v217, 0x7f7f7f7f
	v_mov_b32_e32 v225, 0x43e00000
	v_writelane_b32 v253, s3, 2
	s_add_u32 s2, s18, 0x4fa00000
	s_addc_u32 s3, s19, 0
	v_writelane_b32 v253, s2, 3
	v_mov_b64_e32 v[226:227], 0x2ff
	v_mov_b32_e32 v222, 0x41b17218
	v_writelane_b32 v253, s3, 4
	s_add_u32 s2, s18, 0x4fb00000
	s_addc_u32 s3, s19, 0
	v_writelane_b32 v253, s2, 5
	v_mbcnt_hi_u32_b32 v223, -1, v76
	v_mov_b32_e32 v224, 0xf149f2ca
	v_writelane_b32 v253, s3, 6
	s_add_u32 s2, s18, 0x200000
	v_writelane_b32 v253, s2, 7
	s_addc_u32 s2, s19, 0
	s_cmpk_lt_i32 s97, 0x580
	v_writelane_b32 v253, s2, 8
	s_cselect_b64 s[2:3], -1, 0
	v_writelane_b32 v253, s2, 9
	s_ashr_i32 s21, s97, 31
	s_movk_i32 s75, 0xc0
	v_writelane_b32 v253, s3, 10
	s_lshr_b32 s2, s21, 29
	s_add_i32 s3, s97, s2
	s_ashr_i32 s2, s3, 3
	s_and_b32 s3, s3, -8
	s_sub_i32 s5, s97, s3
	s_ashr_i32 s3, s95, 31
	s_add_u32 s6, s18, 0x4200
	v_writelane_b32 v253, s3, 11
	s_addc_u32 s7, s19, 0
	v_writelane_b32 v253, s6, 12
	s_movk_i32 s76, 0x300
	s_movk_i32 s77, 0x5400
	v_writelane_b32 v253, s7, 13
	s_add_u32 s6, s18, 0x4400
	s_addc_u32 s7, s19, 0
	v_writelane_b32 v253, s6, 14
	s_movk_i32 s81, 0x7fff
	s_mov_b32 s82, 0xffff0000
	v_writelane_b32 v253, s7, 15
	s_add_u32 s6, s18, 0x4500
	s_addc_u32 s7, s19, 0
	v_writelane_b32 v253, s6, 16
	s_movk_i32 s61, 0x1110
	s_movk_i32 s84, 0x15ff
	v_writelane_b32 v253, s7, 17
	s_add_u32 s6, s18, 0x4600
	s_addc_u32 s7, s19, 0
	v_writelane_b32 v253, s6, 18
	s_mov_b32 s85, 0xc3e00000
	s_movk_i32 s33, 0xff
	v_writelane_b32 v253, s7, 19
	s_add_u32 s6, s18, 0x4700
	s_addc_u32 s7, s19, 0
	v_writelane_b32 v253, s6, 20
	s_movk_i32 s66, 0x90
	s_mov_b32 s96, 0x2aaaaaab
	v_writelane_b32 v253, s7, 21
	s_add_u32 s6, s18, 0x4800
	s_addc_u32 s7, s19, 0
	v_writelane_b32 v253, s6, 22
	s_movk_i32 s36, 0x190
	s_movk_i32 s37, 0xff40
	v_writelane_b32 v253, s7, 23
	s_add_u32 s6, s18, 0x4900
	s_addc_u32 s7, s19, 0
	v_writelane_b32 v253, s6, 24
	s_movk_i32 s38, 0x567
	s_movk_i32 s39, 0x1500
	v_writelane_b32 v253, s7, 25
	s_add_u32 s6, s18, 0x4a00
	s_addc_u32 s7, s19, 0
	v_writelane_b32 v253, s6, 26
	s_movk_i32 s56, 0x1800
	s_movk_i32 s57, 0xc80
	v_writelane_b32 v253, s7, 27
	s_add_u32 s6, s18, 0x4b00
	s_addc_u32 s7, s19, 0
	v_writelane_b32 v253, s6, 28
	s_movk_i32 s58, 0x3ff
	s_mov_b32 s80, 0xefa18f08
	v_writelane_b32 v253, s7, 29
	s_add_u32 s6, s18, 0x4c00
	s_addc_u32 s7, s19, 0
	v_writelane_b32 v253, s6, 30
	s_mov_b32 s62, 0
	s_mov_b32 s94, 0x3e000000
	v_writelane_b32 v253, s7, 31
	s_add_u32 s6, s18, 0x4d00
	s_addc_u32 s7, s19, 0
	v_writelane_b32 v253, s6, 32
	s_waitcnt lgkmcnt(0)
	s_barrier
; __global__ void __launch_bounds__(NWAVES * 64, 2) mega_fwd(Args A) {
;     ...
;                 if (std256) { do16 = part == 0 || (part == 1 && bx < 64); i16 = part ? 2 : 0; n16 = part ? 1 : 2;
;                               do8 = (part == 1 && bx >= 64) || (part == 2 && bx < 128); g8 = part == 1 ? 192 : 128; c8 = part == 1 ? bx - 64 : bx; i8 = part == 1 ? 0 : 3; n8 = part == 1 ? 2 : 3; }
;                 else { do16 = part == 0; i16 = 0; n16 = 1 << 20; do8 = part == 1; g8 = G; c8 = bx; i8 = 0; n8 = 1 << 20; }
;                 if (do16) { pg8::Gemm g{H, (const bf16*)(wl + LW_WIN), NTOK, C_GATE, DM}; pg8::RangeOrder S; S.init(NTOK, C_GATE, G, bx); S.i0 = i16; S.n = n16;
;                     pg8::EpiProj E{PROJ, NPROJ, (const float*)A.in[7] + (size_t)l * 6144, 1 << 20, ssq, 1.0f};
;                     pg8::gemm_phase<pg8::EpiProj, pg8::RangeOrder, true, true>(lds + RING_OFF, g, S, E); }
;                 if (do8) { pg8::Gemm g{(const bf16*)XB8, (const bf16*)(wl + LW_WIN + WIN8_OFF), NTOK, 6144, DM / 2}; pg8::RangeOrder S; S.init(NTOK, 6144, g8, c8); S.i0 = i8; S.n = n8;
;                     pg8::EpiGate8 E{(unsigned char*)(PROJ + C_GATE), NPROJ * 2, (const float*)A.in[7] + (size_t)l * 6144, ssq, 1.0f / 2048.0f};
;                     pg8::gemm_phase<pg8::EpiGate8, pg8::RangeOrder, true, true, true>(lds + RING_OFF, g, S, E); }
;                 if (part == 1) xcd_barrier(bar);
;                 if (part == 2 && (!std256 || bx >= 128)) { const int mb = std256 ? bx - 128 : bx, ms = std256 ? 128 : G;
;                     if ((ms & 3) == 0) pool_units(lds, PROJ, (const bf16*)(ws + WS_WPT) + (size_t)l * 4 * 192 * 192, Y + (size_t)NTOK * BRW, mb, ms, 512);
;                     else for (int u = mb; u < 512; u += ms) pool_units(lds, PROJ, (const bf16*)(ws + WS_WPT) + (size_t)l * 4 * 192 * 192, Y + (size_t)NTOK * BRW, u, 512, 512);
;                     gla_pre_items(lds, PROJ, (const float*)A.in[11] + (size_t)l * 16 * 384, (const float*)A.in[12] + l * 384, ws + WS_GPRE, mb, ms, 512); }
;             }
;             xcd_barrier(bar);
;             if (G > 96) { if (bx < 48) gla_scan_unit(lds, ws + WS_GPRE, GO, bx);
;                           else for (int u = bx - 48; u < 256; u += G - 48) att_unit(lds, PROJ, COS, SIN, (const float*)A.in[8] + l * 12, Y, u); }
;             else { for (int u = bx; u < 48; u += G) gla_scan_unit(lds, ws + WS_GPRE, GO, u);
	v_writelane_b32 v253, s7, 33
	s_add_u32 s6, s18, 0x4e00
	s_addc_u32 s7, s19, 0
	v_writelane_b32 v253, s6, 34
	s_nop 1
	v_writelane_b32 v253, s7, 35
	s_add_u32 s6, s18, 0x4f00
	s_addc_u32 s7, s19, 0
	v_writelane_b32 v253, s6, 36
	s_nop 1
	v_writelane_b32 v253, s7, 37
	s_add_u32 s6, s18, 0x5000
	s_addc_u32 s7, s19, 0
	v_writelane_b32 v253, s6, 38
	s_nop 1
	v_writelane_b32 v253, s7, 39
	s_add_u32 s6, s18, 0x5100
	s_addc_u32 s7, s19, 0
	v_writelane_b32 v253, s6, 40
	s_nop 1
	v_writelane_b32 v253, s7, 41
	s_add_u32 s6, s18, 0x5200
	s_addc_u32 s7, s19, 0
	v_writelane_b32 v253, s6, 42
	s_nop 1
	v_writelane_b32 v253, s7, 43
	s_add_u32 s6, s18, 0x5300
	s_addc_u32 s7, s19, 0
	v_writelane_b32 v253, s6, 44
	s_nop 1
	v_writelane_b32 v253, s7, 45
	s_add_u32 s6, s18, 0x7400
	s_addc_u32 s7, s19, 0
	v_writelane_b32 v253, s6, 46
	s_nop 1
	v_writelane_b32 v253, s7, 47
	s_add_u32 s6, s18, 0x7500
	s_addc_u32 s7, s19, 0
	v_writelane_b32 v253, s6, 48
	s_cmpk_eq_i32 s95, 0x100
	s_nop 0
	v_writelane_b32 v253, s7, 49
	s_cselect_b64 s[6:7], -1, 0
	s_add_u32 s72, s18, 0x2fe00000
	s_addc_u32 s73, s19, 0
	v_writelane_b32 v253, s6, 50
	s_cmp_lt_i32 s97, 64
	s_nop 0
	v_writelane_b32 v253, s7, 51
	s_cselect_b64 s[6:7], -1, 0
	v_writelane_b32 v253, s6, 52
	s_cmp_gt_i32 s97, 63
	s_nop 0
	v_writelane_b32 v253, s7, 53
	s_cselect_b64 s[6:7], -1, 0
	v_writelane_b32 v253, s6, 54
	s_cmpk_lt_i32 s97, 0x80
	s_nop 0
	v_writelane_b32 v253, s7, 55
	s_cselect_b64 s[6:7], -1, 0
	v_writelane_b32 v253, s6, 56
	s_sub_i32 s3, s97, 64
	s_nop 0
	v_writelane_b32 v253, s7, 57
	s_add_u32 s6, s18, 0x3b602400
	v_writelane_b32 v253, s3, 58
	s_addc_u32 s7, s19, 0
	v_writelane_b32 v253, s6, 59
	s_cmpk_gt_i32 s97, 0x7f
	s_nop 0
	v_writelane_b32 v253, s7, 60
	s_cselect_b64 s[6:7], -1, 0
	s_mov_b64 s[0:1], -1
	v_writelane_b32 v253, s0, 61
	s_nop 1
	v_writelane_b32 v253, s1, 62
	s_and_b32 s0, s69, 3
	s_cmp_lg_u32 s0, 0
	s_cselect_b64 s[0:1], -1, 0
	v_writelane_b32 v253, s0, 63
	s_cmpk_lt_i32 s20, 0x200
	s_nop 0
	v_writelane_b32 v254, s1, 0
	s_cselect_b64 s[0:1], -1, 0
	v_writelane_b32 v254, s0, 1
	s_nop 1
	v_writelane_b32 v254, s1, 2
	s_add_u32 s0, s18, 0x46a00000
	s_addc_u32 s1, s19, 0
	v_writelane_b32 v254, s0, 3
	s_and_b32 s4, s20, 3
	s_nop 0
	v_writelane_b32 v254, s1, 4
	s_mul_i32 s0, s4, 0x12000
	s_add_u32 s0, s34, s0
	v_writelane_b32 v254, s0, 5
	v_writelane_b32 v254, s34, 6
	s_addc_u32 s0, s35, 0
	s_lshl_b32 s68, 2, s4
	v_writelane_b32 v254, s35, 7
	v_writelane_b32 v254, s0, 8
	s_lshl_b32 s1, s20, 4
	s_lshl_b32 s0, s69, 4
	s_add_u32 s22, s18, 0x4fc00000
	v_writelane_b32 v254, s0, 9
	s_addc_u32 s23, s19, 0
	s_lshl_b32 s0, s20, 6
	s_and_b32 s0, s0, 0x7c0
	v_writelane_b32 v254, s1, 10
	s_and_b32 s1, s1, 0xfffff800
	s_or_b32 s0, s1, s0
	s_ashr_i32 s1, s0, 31
	v_writelane_b32 v254, s0, 11
	s_bfe_u32 s3, s20, 0x20005
	s_mov_b32 s35, 0
	v_writelane_b32 v254, s1, 12
	s_mul_i32 s0, s3, 0x60
	v_writelane_b32 v254, s20, 13
	s_add_i32 s1, s0, 0x920
	v_writelane_b32 v254, s1, 14
	v_writelane_b32 v254, s0, 15
	s_bitset1_b32 s0, 11
	s_cmpk_lt_i32 s95, 0x61
	v_writelane_b32 v254, s0, 16
	s_cselect_b64 s[0:1], -1, 0
	s_cmpk_gt_i32 s95, 0x60
	v_writelane_b32 v254, s0, 17
	s_cselect_b64 s[6:7], -1, 0
	s_cmp_lt_i32 s97, 48
	v_writelane_b32 v254, s1, 18
	s_cselect_b64 s[0:1], -1, 0
	v_writelane_b32 v254, s0, 19
	s_cmpk_lt_i32 s97, 0x100
	s_nop 0
	v_writelane_b32 v254, s1, 20
	s_cselect_b64 s[0:1], -1, 0
	v_writelane_b32 v254, s0, 21
	s_nop 1
	v_writelane_b32 v254, s1, 22
	s_sub_i32 s0, s97, 48
	v_writelane_b32 v254, s0, 23
	s_cmpk_lt_i32 s97, 0x130
	s_mul_hi_i32 s0, s97, 0x55555556
	s_cselect_b64 s[8:9], -1, 0
	s_lshr_b32 s1, s0, 31
	s_add_i32 s10, s0, s1
	s_mul_i32 s0, s10, -3
	s_add_i32 s0, s0, s97
	v_writelane_b32 v254, s8, 24
	s_lshl_b32 s1, s0, 13
	s_add_i32 s1, s1, 0x8000
	v_writelane_b32 v254, s9, 25
	v_writelane_b32 v254, s1, 26
	s_sub_i32 s1, s95, 48
	v_writelane_b32 v254, s1, 27
	s_lshl_b32 s8, s10, 5
	s_mul_i32 s1, s10, 0x1c4000
	v_writelane_b32 v254, s8, 28
	s_mul_hi_i32 s8, s8, 0xe200
	s_add_u32 s14, s22, s1
	s_addc_u32 s15, s23, s8
	s_add_u32 s8, s14, 0xe000
	v_writelane_b32 v254, s14, 29
	s_addc_u32 s9, s15, 0
	s_lshl_b32 s1, s10, 9
	s_lshl_b32 s0, s0, 6
	v_writelane_b32 v254, s15, 30
	s_and_b32 s11, s1, 0xfffff800
	s_ashr_i32 s1, s0, 31
	v_writelane_b32 v254, s8, 31
	s_cmp_gt_i32 s97, 47
	s_nop 0
	v_writelane_b32 v254, s9, 32
	s_cselect_b64 s[8:9], -1, 0
	v_writelane_b32 v254, s8, 33
	s_mov_b64 s[14:15], s[6:7]
	s_add_i32 s6, s97, s95
	s_addk_i32 s6, 0xffa0
	v_writelane_b32 v254, s9, 34
	s_cmpk_lt_i32 s6, 0x100
	s_cselect_b32 s8, 2, 4
	v_writelane_b32 v254, s14, 35
	s_and_b64 s[6:7], s[14:15], exec
	s_cselect_b32 s6, s8, 0
	v_writelane_b32 v254, s15, 36
	v_writelane_b32 v254, s6, 37
	s_add_u32 s6, s18, 0x47600000
	v_writelane_b32 v254, s6, 38
	s_addc_u32 s6, s19, 0
	v_writelane_b32 v254, s6, 39
	s_lshl_b32 s14, s95, 5
	s_lshl_b32 s6, s5, 5
	s_cmp_lt_i32 s5, 0
	s_movk_i32 s7, 0xb1
;     __host__ __device__ bool next(int i, Unit& u) const {
;         const long L = (long)i * G + c; if (L >= nwg) return false;
;         int wgid = (int)L; { const int q = nwg / NXCD, r = nwg % NXCD, xcd = wgid % NXCD, off = wgid / NXCD; wgid = (xcd < r ? xcd * (q + 1) : r * (q + 1) + (xcd - r) * q) + off; }
;         const int nig = WGM * nN, gid = wgid / nig, fm = gid * WGM, gsz = (nM - fm) < WGM ? (nM - fm) : WGM;
;         u.pm = fm + ((wgid % nig) % gsz); u.pn = (wgid % nig) / gsz; u.seg = 0; return true;
; __global__ void __launch_bounds__(NWAVES * 64, 2) mega_fwd(Args A) {
;     ...
;             { const int rem1 = ((NTOK / 256) * (NWI / 256)) % G;
;               conv_until(A, lds, l * TL_LAYER + (kind == 0 ? TL_WIN : TL_LAYER), (rem1 != 0 && bx >= rem1) ? 3 : 0); }
	s_cselect_b32 s7, s7, 0xb0
	s_mul_i32 s7, s5, s7
	s_mul_i32 s5, s5, 33
	s_cselect_b32 s5, s5, s6
	s_add_i32 s7, s7, s2
	s_mul_hi_i32 s6, s7, 0x2e8ba2e9
	s_lshr_b32 s8, s6, 31
	s_ashr_i32 s6, s6, 6
	s_add_i32 s6, s6, s8
	s_mul_i32 s8, s6, 0x160
	s_sub_i32 s7, s7, s8
	s_bfe_u32 s8, s7, 0x3001c
	s_add_i32 s8, s7, s8
	s_and_b32 s9, s8, 0xfff8
	s_sub_i32 s7, s7, s9
	s_lshl_b32 s6, s6, 3
	s_sext_i32_i16 s8, s8
	s_sext_i32_i16 s7, s7
	s_add_i32 s16, s6, s7
	s_ashr_i32 s6, s8, 3
	v_writelane_b32 v254, s6, 40
	s_lshr_b32 s6, s8, 3
	s_bfe_i64 s[6:7], s[6:7], 0x100000
	s_lshl_b64 s[6:7], s[6:7], 20
	v_writelane_b32 v254, s6, 41
	s_ashr_i32 s17, s16, 31
	s_nop 0
	v_writelane_b32 v254, s7, 42
	s_mov_b32 s6, s16
	v_writelane_b32 v254, s6, 43
	s_nop 1
	v_writelane_b32 v254, s7, 44
	s_lshl_b64 s[6:7], s[16:17], 20
	s_add_u32 s6, s90, s6
	s_addc_u32 s7, s91, s7
	s_add_u32 s8, s6, 0x80000
	s_addc_u32 s9, s7, 0
	v_writelane_b32 v254, s8, 45
	s_nop 1
	v_writelane_b32 v254, s9, 46
	s_add_u32 s8, s6, 0x2000
	v_writelane_b32 v254, s6, 47
	s_addc_u32 s9, s7, 0
	s_add_i32 s2, s5, s2
	s_ashr_i32 s5, s2, 31
	s_lshr_b32 s5, s5, 26
	s_add_i32 s5, s2, s5
	v_writelane_b32 v254, s7, 48
	s_and_b32 s6, s5, 0xffc0
	s_sub_i32 s2, s2, s6
	s_bfe_i32 s6, s2, 0x80000
	s_bfe_u32 s6, s6, 0x3000c
	s_add_i32 s6, s2, s6
	s_and_b32 s7, s6, 0xf8
	s_sub_i32 s2, s2, s7
	s_ashr_i32 s5, s5, 6
	s_lshl_b32 s5, s5, 3
	s_sext_i32_i8 s2, s2
	s_add_i32 s5, s5, s2
	s_bfe_i32 s2, s6, 0x80000
	v_writelane_b32 v254, s8, 49
	s_sext_i32_i16 s2, s2
	s_ashr_i32 s6, s2, 3
	v_writelane_b32 v254, s9, 50
	s_lshr_b32 s2, s2, 3
	v_writelane_b32 v254, s6, 51
	s_bfe_i64 s[6:7], s[2:3], 0x100000
	v_writelane_b32 v254, s6, 52
	s_mul_hi_i32 s2, s5, 0x60000
	s_nop 0
	v_writelane_b32 v254, s7, 53
	v_writelane_b32 v254, s5, 54
	s_mul_i32 s5, s5, 0x60000
	s_add_u32 s6, s12, s5
	s_addc_u32 s7, s13, s2
	s_add_u32 s8, s6, 0x30000
	s_addc_u32 s9, s7, 0
	v_writelane_b32 v254, s8, 55
	s_nop 1
	v_writelane_b32 v254, s9, 56
	s_add_u32 s8, s6, 0x2000
	v_writelane_b32 v254, s6, 57
	s_addc_u32 s9, s7, 0
	s_abs_i32 s2, s95
	v_cvt_f32_u32_e32 v1, s2
	v_writelane_b32 v254, s7, 58
	s_sub_i32 s5, 0, s2
	v_writelane_b32 v254, s8, 59
	v_rcp_iflag_f32_e32 v1, v1
	s_nop 0
	v_writelane_b32 v254, s9, 60
	v_mul_f32_e32 v1, 0x4f7ffffe, v1
	v_cvt_u32_f32_e32 v1, v1
	s_nop 0
	v_readfirstlane_b32 s6, v1
	s_mul_i32 s5, s5, s6
	s_mul_hi_u32 s5, s6, s5
	s_add_i32 s6, s6, s5
	s_mul_hi_u32 s5, s6, 0x580
	s_mul_i32 s5, s5, s2
	s_sub_i32 s5, 0x580, s5
	s_sub_i32 s6, s5, s2
	s_cmp_ge_u32 s5, s2
	s_cselect_b32 s5, s6, s5
	s_sub_i32 s6, s5, s2
	s_cmp_ge_u32 s5, s2
	s_cselect_b32 s2, s6, s5
	s_cmp_lg_u32 s2, 0
	s_cselect_b64 s[6:7], -1, 0
	s_cmp_ge_i32 s97, s2
	s_cselect_b64 s[8:9], -1, 0
	s_and_b64 s[6:7], s[6:7], s[8:9]
	s_mul_i32 s2, s4, 0xc0
	v_writelane_b32 v254, s6, 61
	s_and_b64 s[4:5], s[6:7], exec
	s_cselect_b32 s4, 3, 0
	v_writelane_b32 v254, s7, 62
	v_writelane_b32 v255, s2, 0
	s_lshl_b32 s2, s2, 1
	v_writelane_b32 v254, s4, 63
	s_add_u32 s4, s88, s2
	s_addc_u32 s5, s89, 0
	v_writelane_b32 v255, s4, 1
	s_and_b32 s2, s10, 3
	s_mulk_i32 s2, 0x300
	v_writelane_b32 v255, s5, 2
	s_mul_i32 s4, s11, 0xc00
	s_lshl_b32 s5, s97, 6
	s_or_b32 s2, s4, s2
	s_lshl_b64 s[0:1], s[0:1], 2
	v_writelane_b32 v255, s5, 3
	s_lshl_b32 s5, s95, 6
	s_mul_hi_i32 s4, s11, 0xc00
	s_add_u32 s0, s2, s0
	s_addc_u32 s1, s4, s1
	s_add_u32 s0, s18, s0
	v_writelane_b32 v255, s5, 4
	s_addc_u32 s1, s19, s1
	v_writelane_b32 v255, s0, 5
	s_mul_i32 s2, s95, 0x18000
	s_add_i32 s93, 0, 0x20180
	v_writelane_b32 v255, s1, 6
	s_mul_i32 s0, s3, 0xc0
	s_mul_hi_i32 s3, s14, 0xc00
	v_writelane_b32 v255, s2, 7
	s_lshl_b32 s1, s97, 9
	s_lshl_b32 s0, s0, 1
	v_writelane_b32 v255, s3, 8
	s_mul_i32 s2, s95, 0xa8000
	v_writelane_b32 v255, s14, 9
	s_mul_hi_i32 s3, s14, 0x5400
	v_writelane_b32 v255, s2, 10
	s_add_i32 s60, 0, 0x20184
	v_mov_b32_e32 v1, 0x358637bd
	v_writelane_b32 v255, s3, 11
	v_writelane_b32 v255, s1, 12
	s_lshl_b32 s1, s95, 11
	v_writelane_b32 v255, s1, 13
	s_lshl_b32 s1, s95, 4
	v_writelane_b32 v255, s1, 14
	s_lshl_b32 s1, s95, 10
	v_writelane_b32 v255, s1, 15
	s_lshl_b32 s1, s95, 9
	v_writelane_b32 v255, s1, 16
	s_add_i32 s1, 0, 0x20160
	v_writelane_b32 v255, s1, 17
	s_add_i32 s1, 0, 0x20164
	v_writelane_b32 v255, s1, 18
	s_add_i32 s1, 0, 0x2d00
	v_writelane_b32 v255, s1, 19
	v_writelane_b32 v255, s0, 20
	s_add_i32 s64, 0, 0x12600
	s_nop 0
	v_writelane_b32 v255, s1, 21
	s_add_i32 s0, 0, 0xf000
	v_writelane_b32 v255, s0, 22
	s_add_i32 s0, 0, 0x8800
	v_writelane_b32 v255, s0, 23
	v_writelane_b32 v255, s90, 24
	s_nop 1
	v_writelane_b32 v255, s91, 25
	v_writelane_b32 v255, s69, 26
	v_writelane_b32 v255, s88, 27
	s_nop 1
	v_writelane_b32 v255, s89, 28
	v_writelane_b32 v255, s21, 29
	v_writelane_b32 v255, s22, 30
	v_writelane_b32 v255, s23, 31
	v_writelane_b32 v255, s93, 32
	v_writelane_b32 v255, s60, 33
	v_writelane_b32 v255, s92, 34
	s_nop 1
	v_writelane_b32 v255, s93, 35
	s_branch .LBB0_287

; __global__ void __launch_bounds__(NWAVES * 64, 2) mega_fwd(Args A) {
;     ...
;                 if (std256) { do16 = part == 0 || (part == 1 && bx < 64); i16 = part ? 2 : 0; n16 = part ? 1 : 2;
;                               do8 = (part == 1 && bx >= 64) || (part == 2 && bx < 128); g8 = part == 1 ? 192 : 128; c8 = part == 1 ? bx - 64 : bx; i8 = part == 1 ? 0 : 3; n8 = part == 1 ? 2 : 3; }
;                 else { do16 = part == 0; i16 = 0; n16 = 1 << 20; do8 = part == 1; g8 = G; c8 = bx; i8 = 0; n8 = 1 << 20; }
.LBB0_550:
	s_cmp_eq_u32 s63, 0
	v_readlane_b32 s4, v253, 50
	s_cselect_b64 s[2:3], -1, 0
	s_cmp_eq_u32 s63, 1
	v_readlane_b32 s5, v253, 51
	s_cselect_b64 s[0:1], -1, 0
	s_andn2_b64 vcc, exec, s[4:5]
	s_cbranch_vccnz .LBB0_552
	v_readlane_b32 s4, v253, 52
	v_readlane_b32 s5, v253, 53
	s_and_b64 s[4:5], s[4:5], s[0:1]
	s_or_b64 s[4:5], s[2:3], s[4:5]
	s_and_b64 s[2:3], s[2:3], exec
	v_readlane_b32 s2, v253, 54
	v_readlane_b32 s3, v253, 55
	s_cselect_b32 s40, 0, 2
	s_cselect_b32 s26, 2, 1
	s_and_b64 s[2:3], s[2:3], s[0:1]
	s_cmp_eq_u32 s63, 2
	v_readlane_b32 s8, v253, 56
	s_cselect_b64 s[6:7], -1, 0
	v_readlane_b32 s9, v253, 57
	s_mov_b64 s[6:7], 0
	s_or_b64 s[2:3], s[2:3], s[6:7]
	s_and_b64 s[0:1], s[0:1], exec
	v_readlane_b32 s0, v253, 58
	s_cselect_b32 s42, s75, 0x80
	s_cselect_b32 s54, s0, s97
	s_cselect_b32 s25, 0, 3
	s_cselect_b32 s24, 4, 3
	s_mov_b64 s[0:1], s[2:3]
	s_mov_b64 s[2:3], s[4:5]
	s_andn2_b64 vcc, exec, s[2:3]
	s_cbranch_vccz .LBB0_553
	s_branch .LBB0_570
